# attention: context unit before latent unit on workgroups 0-15 (guarded for a 256-workgroup grid)
# speedup vs baseline: 1.0053x; 1.0053x over previous
; #define LAS __attribute__((address_space(3)))
; __device__ __forceinline__ void attn_mfma(LAS unsigned char* lds, int layer, int G, const int wave_s) {
;     ...
;     const bf16_t* Q = (const bf16_t*)(ws + WS_Q); const bf16_t* Kb = (const bf16_t*)(ws + WS_K); const bf16_t* Vb = (const bf16_t*)(ws + WS_V);
;     bf16_t* YM = (bf16_t*)(ws + WS_YM); const float* ZT = (const float*)(ws + WS_SSHY);
;     const float* gat = Pp->in[20] + layer * ATTW; const float* ghy = Pp->in[19] + layer * HY;
;     const int r32 = lane & 31, hi = lane >> 5, h = wave, kv = h >> 2;
;     const float sk = Pp->in[18][layer * NH + h] * LOG2E;
;     const unsigned lbase = (unsigned)(uintptr_t)lds;
;     LAS float* al_l = (LAS float*)(lds + AT_SCR) + wave * 64; LAS float* li_l = al_l + 32;
;     LAS float* xa = (LAS float*)(lds + AT_XA); LAS float* xh = (LAS float*)(lds + AT_XH);
;     const int nunits = layer == DEPTH - 1 ? ML / 32 : MT / 32;
;     for (int unit = blockIdx.x; unit < nunits; unit += G) {
.LBB0_785:
	s_andn2_b64 vcc, exec, s[36:37]
	s_cbranch_vccnz .LBB0_884
	s_cmp_lg_u32 s76, 3
	s_cselect_b64 s[44:45], -1, 0
	s_and_b64 s[0:1], s[44:45], exec
	s_movk_i32 s0, 0x110
	s_cselect_b32 s0, s0, 0x100
	s_cmp_ge_i32 s2, s0
	v_readlane_b32 s17, v253, 2
	s_mov_b64 s[36:37], s[94:95]
	v_mbcnt_lo_u32_b32 v0, -1, 0
	v_mbcnt_hi_u32_b32 v0, -1, v0
	s_cbranch_scc1 .LBB0_826
	s_load_dwordx2 s[40:41], s[36:37], 0xd8
	s_lshl_b32 s10, s76, 3
	s_lshl_b32 s1, s17, 6
	v_and_b32_e32 v184, 31, v0
	s_waitcnt vmcnt(0)
	v_lshlrev_b32_e32 v4, 4, v0
	s_waitcnt lgkmcnt(0)
	s_add_u32 s46, s40, 0xac20000
	s_addc_u32 s47, s41, 0
	s_add_u32 s48, s40, 0xb060000
	s_addc_u32 s49, s41, 0
	s_add_u32 s42, s40, 0xb4a0000
	s_addc_u32 s43, s41, 0
	s_add_i32 s10, s17, s10
	s_ashr_i32 s11, s10, 31
	s_lshl_b64 s[38:39], s[10:11], 2
	s_load_dwordx2 s[10:11], s[36:37], 0x90
	s_load_dwordx4 s[52:55], s[36:37], 0x98
	v_and_b32_e32 v6, 0xc0, v4
	v_lshlrev_b32_e32 v7, 1, v0
	v_and_b32_e32 v7, 32, v7
	s_waitcnt lgkmcnt(0)
	s_add_u32 s10, s10, s38
	s_addc_u32 s11, s11, s39
	global_load_dword v2, v1, s[10:11]
	s_lshl_b32 s10, s17, 8
	s_add_i32 s15, s10, 0
	s_lshl_b32 s26, s76, 10
	s_add_i32 s15, s15, 0x20000
	s_lshl_b64 s[10:11], s[26:27], 2
	s_add_u32 s56, s52, s10
	s_addc_u32 s57, s53, s11
	s_add_u32 s54, s54, s10
	s_addc_u32 s55, s55, s11
	s_lshl_b32 s60, s17, 7
	s_ashr_i32 s61, s60, 31
	s_lshl_b64 s[52:53], s[60:61], 1
	s_add_u32 s10, s40, s52
	s_addc_u32 s11, s41, s53
	s_add_u32 s50, s10, 0x9b20000
	s_addc_u32 s51, s11, 0
	s_lshl_b32 s10, s17, 12
	s_and_b32 s10, s10, 0xffffc000
	s_add_i32 s11, s10, 0
	v_lshl_add_u32 v188, v184, 8, s11
	s_add_i32 s11, 0, 0x8000
	v_add_u32_e32 v6, s11, v6
	v_ashrrev_i32_e32 v185, 5, v0
	v_mov_b32_e32 v163, v1
	s_mulk_i32 s17, 0x2200
	v_lshlrev_b32_e32 v187, 4, v185
	v_cmp_gt_u32_e64 s[36:37], 32, v0
	s_mov_b64 s[28:29], 0xd6a0000
	s_add_i32 s17, s17, 0
	v_ashrrev_i32_e32 v194, 4, v0
	v_lshl_add_u32 v193, v184, 1, s17
	v_lshlrev_b32_e32 v189, 2, v185
	v_lshlrev_b32_e32 v5, 2, v184
	v_readlane_b32 s23, v255, 7
	s_add_i32 s11, s60, 0
	s_add_i32 s11, s11, 0x20c00
	v_add_u32_e32 v190, s15, v5
	v_add_u32_e32 v209, s15, v187
	s_movk_i32 s15, 0x440
	v_cmp_eq_u32_e64 s[38:39], 0, v184
	s_waitcnt vmcnt(0)
	v_mul_f32_e32 v186, 0x3fb8aa3b, v2
	v_lshlrev_b32_e32 v2, 3, v0
	v_and_b32_e32 v3, 24, v2
	v_and_b32_e32 v2, 0x100, v2
	v_add3_u32 v3, v6, v3, v7
	v_add3_u32 v191, v3, v2, s10
	v_and_b32_e32 v2, 7, v0
	v_lshlrev_b32_e32 v162, 4, v2
	v_and_b32_e32 v6, -8, v0
	v_lshlrev_b32_e32 v192, 2, v2
	v_lshl_add_u64 v[2:3], s[40:41], 0, v[162:163]
	v_cmp_gt_i32_e64 s[40:41], 8, v0
	v_and_b32_e32 v0, 0xf0, v4
	v_lshl_add_u64 v[164:165], v[2:3], 0, s[28:29]
	v_add_u32_e32 v196, s17, v0
	s_movk_i32 s17, 0x70
	v_add_u32_e32 v3, 32, v187
	v_bitop3_b32 v202, v3, v4, s17 bitop3:0x78
	v_add_u32_e32 v3, 64, v187
	v_bitop3_b32 v203, v3, v4, s17 bitop3:0x78
	v_add_u32_e32 v3, 0x60, v187
	v_bitop3_b32 v204, v3, v4, s17 bitop3:0x78
	v_add_u32_e32 v3, 0x80, v187
	v_bitop3_b32 v205, v3, v4, s17 bitop3:0x78
	v_add_u32_e32 v3, 0xa0, v187
	v_bitop3_b32 v206, v3, v4, s17 bitop3:0x78
	v_add_u32_e32 v3, 0xc0, v187
	v_bitop3_b32 v207, v3, v4, s17 bitop3:0x78
	v_add_u32_e32 v3, 0xe0, v187
	v_or_b32_e32 v2, s60, v184
	v_bitop3_b32 v200, v187, v4, s17 bitop3:0x78
	v_bitop3_b32 v208, v3, v4, s17 bitop3:0x78
	v_add_u32_e32 v4, s1, v6
	s_mov_b32 s17, 0x8800
	v_add_u32_e32 v6, 0x200, v4
	v_ashrrev_i32_e32 v3, 31, v2
	s_add_i32 s10, s23, s60
	v_add_u32_e32 v163, s23, v5
	s_movk_i32 s23, 0x110
	v_mad_i64_i32 v[166:167], s[28:29], v4, s17, 0
	v_mad_i64_i32 v[168:169], s[28:29], v6, s17, 0
	v_lshl_add_u64 v[180:181], v[2:3], 2, s[54:55]
	v_or_b32_e32 v3, 1, v189
	v_mul_lo_u32 v198, v194, s23
	v_ashrrev_i32_e32 v5, 31, v4
	v_mul_lo_u32 v210, v3, s23
	s_add_u32 s28, s42, s52
	v_ashrrev_i32_e32 v7, 31, v6
	v_lshl_add_u64 v[174:175], v[4:5], 2, s[56:57]
	v_lshl_add_u64 v[176:177], v[4:5], 1, s[42:43]
	v_mul_lo_u32 v2, v185, s15
	v_add_u32_e32 v3, 0x990, v210
	v_add_u32_e32 v4, 0x440, v198
	s_addc_u32 s29, s43, s53
	v_lshl_add_u64 v[178:179], v[6:7], 1, s[42:43]
	v_lshl_add_u64 v[182:183], s[28:29], 0, v[0:1]
	v_add_u32_e32 v211, v193, v2
	v_add_u32_e32 v212, v193, v3
	v_add_u32_e32 v213, v196, v4
	v_mbcnt_lo_u32_b32 v66, -1, 0
	v_mbcnt_hi_u32_b32 v66, -1, v66
	v_add_u32_e32 v67, s1, v66
	v_ashrrev_i32_e32 v68, 4, v67
	v_and_b32_e32 v70, 0xfffff0, v68
	v_lshlrev_b32_e32 v71, 1, v68
	v_lshlrev_b32_e32 v66, 3, v66
	v_and_or_b32 v70, v71, 8, v70
	v_and_b32_e32 v69, 0x78, v66
	v_lshrrev_b32_e32 v70, 1, v70
	v_bfe_u32 v66, v66, 5, 2
	v_lshrrev_b32_e32 v71, 1, v68
	v_or_b32_e32 v66, v70, v66
	v_and_b32_e32 v70, 3, v68
	v_lshlrev_b32_e32 v69, 1, v69
	v_and_or_b32 v70, v71, 4, v70
	v_and_b32_e32 v71, 48, v69
	v_lshlrev_b32_e32 v68, 8, v68
	v_and_b32_e32 v67, 0x70, v67
	v_lshl_or_b32 v70, v70, 6, v71
	v_bitop3_b32 v67, v69, v68, v67 bitop3:0xde
	v_lshl_or_b32 v66, v66, 9, v70
	v_mov_b32_e32 v233, v67
	v_mov_b32_e32 v234, v66
	v_mbcnt_lo_u32_b32 v236, -1, 0
	v_mbcnt_hi_u32_b32 v236, -1, v236
	v_add_u32_e32 v235, s1, v236
	v_ashrrev_i32_e32 v235, 4, v235
	v_lshlrev_b32_e32 v236, 4, v236
	v_and_b32_e32 v236, 0xf0, v236
	s_mov_b32 s15, s2
	s_cmpk_lg_u32 s3, 0x100
	s_cbranch_scc1 .Lcf_e
	s_add_i32 s15, s2, s3
	s_cmp_lt_i32 s15, s0
	s_cselect_b32 s15, s15, s2

; #define LAS __attribute__((address_space(3)))
; __device__ __forceinline__ unsigned f2bf(float f) { unsigned u = __builtin_bit_cast(unsigned, f); return (u + 0x7fffu + ((u >> 16) & 1u)) >> 16; }
; __device__ __forceinline__ int crow(int r, int hi) { return (r & 3) + 8 * (r >> 2) + 4 * hi; }
; __device__ __forceinline__ void attn_mfma(LAS unsigned char* lds, int layer, int G, const int wave_s) {
;     ...
;     for (int unit = blockIdx.x; unit < nunits; unit += G) {
;     ...
;         if (hi == 0) al_l[r32] = ra; asm volatile("s_waitcnt lgkmcnt(0)" ::: "memory");
;         { LAS unsigned char* ost = lds + AT_OST + wave * (32 * 272);
;           float gc[4];
; #pragma unroll
;           for (int d = 0; d < 4; ++d) gc[d] = gat[h * HD + 32 * d + r32];
; #pragma unroll
;           for (int r = 0; r < 16; ++r) { const int q = crow(r, hi); const float rq = al_l[q];
; #pragma unroll
;               for (int d = 0; d < 4; ++d) *(LAS bf16_t*)(ost + q * 272 + (32 * d + r32) * 2) = (bf16_t)f2bf(o[d][r] * rq * gc[d]); }
;           asm volatile("s_waitcnt lgkmcnt(0)" ::: "memory");
; #pragma unroll
;           for (int k = 0; k < 8; ++k) { const int q = k * 4 + (lane >> 4), ch = lane & 15;
;               const u32x4 v = *(const LAS u32x4*)(ost + q * 272 + ch * 16);
;               *(u32x4*)(YM + (size_t)(rowbase + q) * D + HY + h * HD + ch * 8) = v; } }
.LBB0_788:
	s_or_b64 exec, exec, s[54:55]
	s_waitcnt lgkmcnt(0)
	global_load_dword v8, v[180:181], off
	global_load_dword v7, v[180:181], off offset:128
	global_load_dword v6, v[180:181], off offset:256
	global_load_dword v0, v[180:181], off offset:384
	ds_read_b128 v[2:5], v209
	s_cmpk_lg_u32 s3, 0x100
	s_cbranch_scc1 .Lcf_o
	s_sub_i32 s4, s15, s3
	s_lshl_b32 s5, s3, 1
	s_add_i32 s5, s15, s5
	s_cmp_ge_i32 s15, s3
	s_cselect_b32 s15, s4, s5
	s_branch .Lcf_n
.Lcf_o:
	s_add_i32 s15, s15, s3
.Lcf_n:
	s_cmp_lt_i32 s15, s0
	s_waitcnt lgkmcnt(0)
	v_mul_f32_e32 v9, v140, v2
	s_waitcnt vmcnt(3)
	v_mul_f32_e32 v9, v8, v9
	v_bfe_u32 v10, v9, 16, 1
	v_add3_u32 v9, v9, v10, s66
	ds_write_b16_d16_hi v211, v9
	v_mul_f32_e32 v9, v130, v2
	s_waitcnt vmcnt(2)
	v_mul_f32_e32 v9, v7, v9
	v_bfe_u32 v10, v9, 16, 1
	v_add3_u32 v9, v9, v10, s66
	ds_write_b16_d16_hi v211, v9 offset:64
	v_mul_f32_e32 v9, v128, v2
	s_waitcnt vmcnt(1)
	v_mul_f32_e32 v9, v6, v9
	v_bfe_u32 v10, v9, 16, 1
	v_mul_f32_e32 v2, v126, v2
	v_add3_u32 v9, v9, v10, s66
	s_waitcnt vmcnt(0)
	v_mul_f32_e32 v2, v0, v2
	ds_write_b16_d16_hi v211, v9 offset:128
	v_bfe_u32 v9, v2, 16, 1
	v_add3_u32 v2, v2, v9, s66
	ds_write_b16_d16_hi v211, v2 offset:192
	v_mul_f32_e32 v2, v141, v3
	v_mul_f32_e32 v2, v8, v2
	v_bfe_u32 v9, v2, 16, 1
	v_add3_u32 v2, v2, v9, s66
	v_add_u32_e32 v9, v193, v210
	ds_write_b16_d16_hi v9, v2
	v_mul_f32_e32 v2, v131, v3
	v_mul_f32_e32 v2, v7, v2
	v_bfe_u32 v10, v2, 16, 1
	v_add3_u32 v2, v2, v10, s66
	ds_write_b16_d16_hi v9, v2 offset:64
	v_mul_f32_e32 v2, v129, v3
	v_mul_f32_e32 v2, v6, v2
	v_bfe_u32 v10, v2, 16, 1
	v_add3_u32 v2, v2, v10, s66
	ds_write_b16_d16_hi v9, v2 offset:128
	v_mul_f32_e32 v2, v127, v3
	v_mul_f32_e32 v2, v0, v2
	v_bfe_u32 v3, v2, 16, 1
	v_add3_u32 v2, v2, v3, s66
	ds_write_b16_d16_hi v9, v2 offset:192
	v_mul_f32_e32 v2, v138, v4
	v_mul_f32_e32 v2, v8, v2
	v_bfe_u32 v3, v2, 16, 1
	v_add3_u32 v2, v2, v3, s66
	ds_write_b16_d16_hi v9, v2 offset:272
	v_mul_f32_e32 v2, v134, v4
	v_mul_f32_e32 v2, v7, v2
	v_bfe_u32 v3, v2, 16, 1
	v_add3_u32 v2, v2, v3, s66
	ds_write_b16_d16_hi v9, v2 offset:336
	v_mul_f32_e32 v2, v136, v4
	v_mul_f32_e32 v2, v6, v2
	v_bfe_u32 v3, v2, 16, 1
	v_add3_u32 v2, v2, v3, s66
	ds_write_b16_d16_hi v9, v2 offset:400
	v_mul_f32_e32 v2, v132, v4
	v_mul_f32_e32 v2, v0, v2
	v_bfe_u32 v3, v2, 16, 1
	v_add3_u32 v2, v2, v3, s66
	ds_write_b16_d16_hi v9, v2 offset:464
	v_mul_f32_e32 v2, v139, v5
	v_mul_f32_e32 v2, v8, v2
	v_bfe_u32 v3, v2, 16, 1
	v_add3_u32 v2, v2, v3, s66
	ds_write_b16_d16_hi v9, v2 offset:544
	v_mul_f32_e32 v2, v135, v5
	v_mul_f32_e32 v2, v7, v2
	v_bfe_u32 v3, v2, 16, 1
	v_add3_u32 v2, v2, v3, s66
	ds_write_b16_d16_hi v9, v2 offset:608
	v_mul_f32_e32 v2, v137, v5
	v_mul_f32_e32 v2, v6, v2
	v_bfe_u32 v3, v2, 16, 1
	v_add3_u32 v2, v2, v3, s66
	ds_write_b16_d16_hi v9, v2 offset:672
	v_mul_f32_e32 v2, v133, v5
	v_mul_f32_e32 v2, v0, v2
	v_bfe_u32 v3, v2, 16, 1
	v_add3_u32 v2, v2, v3, s66
	ds_write_b16_d16_hi v9, v2 offset:736
	ds_read_b128 v[2:5], v209 offset:32
	s_waitcnt lgkmcnt(0)
	v_mul_f32_e32 v10, v100, v2
	v_mul_f32_e32 v10, v8, v10
	v_bfe_u32 v11, v10, 16, 1
	v_add3_u32 v10, v10, v11, s66
	ds_write_b16_d16_hi v9, v10 offset:1904
	v_mul_f32_e32 v10, v96, v2
	v_mul_f32_e32 v10, v7, v10
	v_bfe_u32 v11, v10, 16, 1
	v_add3_u32 v10, v10, v11, s66
	ds_write_b16_d16_hi v9, v10 offset:1968
	v_mul_f32_e32 v10, v98, v2
	v_mul_f32_e32 v10, v6, v10
	v_bfe_u32 v11, v10, 16, 1
	v_mul_f32_e32 v2, v94, v2
	v_add3_u32 v10, v10, v11, s66
	v_mul_f32_e32 v2, v0, v2
	ds_write_b16_d16_hi v9, v10 offset:2032
	v_bfe_u32 v10, v2, 16, 1
	v_add3_u32 v2, v2, v10, s66
	ds_write_b16_d16_hi v9, v2 offset:2096
	v_mul_f32_e32 v2, v101, v3
	v_mul_f32_e32 v2, v8, v2
	v_bfe_u32 v10, v2, 16, 1
	v_add3_u32 v2, v2, v10, s66
	ds_write_b16_d16_hi v9, v2 offset:2176
	v_mul_f32_e32 v2, v97, v3
	v_mul_f32_e32 v2, v7, v2
	v_bfe_u32 v10, v2, 16, 1
	v_add3_u32 v2, v2, v10, s66
	ds_write_b16_d16_hi v9, v2 offset:2240
	v_mul_f32_e32 v2, v99, v3
	v_mul_f32_e32 v2, v6, v2
	v_bfe_u32 v10, v2, 16, 1
	v_add3_u32 v2, v2, v10, s66
	ds_write_b16_d16_hi v9, v2 offset:2304
	v_mul_f32_e32 v2, v95, v3
	v_mul_f32_e32 v2, v0, v2
	v_bfe_u32 v3, v2, 16, 1
	v_add3_u32 v2, v2, v3, s66
	ds_write_b16_d16_hi v9, v2 offset:2368
	v_mul_f32_e32 v2, v108, v4
	v_mul_f32_e32 v2, v8, v2
	v_bfe_u32 v3, v2, 16, 1
	v_add3_u32 v2, v2, v3, s66
	ds_write_b16_d16_hi v9, v2 offset:2448
	v_mul_f32_e32 v2, v104, v4
	v_mul_f32_e32 v2, v7, v2
	v_bfe_u32 v3, v2, 16, 1
	v_add3_u32 v2, v2, v3, s66
	ds_write_b16_d16_hi v212, v2 offset:64
	v_mul_f32_e32 v2, v106, v4
	v_mul_f32_e32 v2, v6, v2
	v_bfe_u32 v3, v2, 16, 1
	v_add3_u32 v2, v2, v3, s66
	ds_write_b16_d16_hi v212, v2 offset:128
	v_mul_f32_e32 v2, v102, v4
	v_mul_f32_e32 v2, v0, v2
	v_bfe_u32 v3, v2, 16, 1
	v_add3_u32 v2, v2, v3, s66
	ds_write_b16_d16_hi v212, v2 offset:192
	v_mul_f32_e32 v2, v109, v5
	v_mul_f32_e32 v2, v8, v2
	v_bfe_u32 v3, v2, 16, 1
	v_add3_u32 v2, v2, v3, s66
	ds_write_b16_d16_hi v212, v2 offset:272
	v_mul_f32_e32 v2, v105, v5
	v_mul_f32_e32 v2, v7, v2
	v_bfe_u32 v3, v2, 16, 1
	v_add3_u32 v2, v2, v3, s66
	ds_write_b16_d16_hi v212, v2 offset:336
	v_mul_f32_e32 v2, v107, v5
	v_mul_f32_e32 v2, v6, v2
	v_bfe_u32 v3, v2, 16, 1
	v_add3_u32 v2, v2, v3, s66
	ds_write_b16_d16_hi v212, v2 offset:400
	v_mul_f32_e32 v2, v103, v5
	v_mul_f32_e32 v2, v0, v2
	v_bfe_u32 v3, v2, 16, 1
	v_add3_u32 v2, v2, v3, s66
	ds_write_b16_d16_hi v212, v2 offset:464
	ds_read_b128 v[2:5], v209 offset:64
	s_waitcnt lgkmcnt(0)
; #define LAS __attribute__((address_space(3)))
; __device__ __forceinline__ unsigned f2bf(float f) { unsigned u = __builtin_bit_cast(unsigned, f); return (u + 0x7fffu + ((u >> 16) & 1u)) >> 16; }
; __device__ __forceinline__ int crow(int r, int hi) { return (r & 3) + 8 * (r >> 2) + 4 * hi; }
; __device__ __forceinline__ void attn_mfma(LAS unsigned char* lds, int layer, int G, const int wave_s) {
;     ...
;         { LAS unsigned char* ost = lds + AT_OST + wave * (32 * 272);
;           float gc[4];
; #pragma unroll
;           for (int d = 0; d < 4; ++d) gc[d] = gat[h * HD + 32 * d + r32];
; #pragma unroll
;           for (int r = 0; r < 16; ++r) { const int q = crow(r, hi); const float rq = al_l[q];
; #pragma unroll
;               for (int d = 0; d < 4; ++d) *(LAS bf16_t*)(ost + q * 272 + (32 * d + r32) * 2) = (bf16_t)f2bf(o[d][r] * rq * gc[d]); }
;           asm volatile("s_waitcnt lgkmcnt(0)" ::: "memory");
; #pragma unroll
;           for (int k = 0; k < 8; ++k) { const int q = k * 4 + (lane >> 4), ch = lane & 15;
;               const u32x4 v = *(const LAS u32x4*)(ost + q * 272 + ch * 16);
;               *(u32x4*)(YM + (size_t)(rowbase + q) * D + HY + h * HD + ch * 8) = v; } }
	v_mul_f32_e32 v9, v124, v2
	v_mul_f32_e32 v9, v8, v9
	v_bfe_u32 v10, v9, 16, 1
	v_add3_u32 v9, v9, v10, s66
	ds_write_b16_d16_hi v212, v9 offset:1632
	v_mul_f32_e32 v9, v122, v2
	v_mul_f32_e32 v9, v7, v9
	v_bfe_u32 v10, v9, 16, 1
	v_add3_u32 v9, v9, v10, s66
	ds_write_b16_d16_hi v212, v9 offset:1696
	v_mul_f32_e32 v9, v120, v2
	v_mul_f32_e32 v9, v6, v9
	v_bfe_u32 v10, v9, 16, 1
	v_mul_f32_e32 v2, v118, v2
	v_add3_u32 v9, v9, v10, s66
	v_mul_f32_e32 v2, v0, v2
	ds_write_b16_d16_hi v212, v9 offset:1760
	v_bfe_u32 v9, v2, 16, 1
	v_add3_u32 v2, v2, v9, s66
	ds_write_b16_d16_hi v212, v2 offset:1824
	v_mul_f32_e32 v2, v125, v3
	v_mul_f32_e32 v2, v8, v2
	v_bfe_u32 v9, v2, 16, 1
	v_add3_u32 v2, v2, v9, s66
	ds_write_b16_d16_hi v212, v2 offset:1904
	v_mul_f32_e32 v2, v123, v3
	v_mul_f32_e32 v2, v7, v2
	v_bfe_u32 v9, v2, 16, 1
	v_add3_u32 v2, v2, v9, s66
	ds_write_b16_d16_hi v212, v2 offset:1968
	v_mul_f32_e32 v2, v121, v3
	v_mul_f32_e32 v2, v6, v2
	v_bfe_u32 v9, v2, 16, 1
	v_add3_u32 v2, v2, v9, s66
	ds_write_b16_d16_hi v212, v2 offset:2032
	v_mul_f32_e32 v2, v119, v3
	v_mul_f32_e32 v2, v0, v2
	v_bfe_u32 v3, v2, 16, 1
	v_add3_u32 v2, v2, v3, s66
	ds_write_b16_d16_hi v212, v2 offset:2096
	v_mul_f32_e32 v2, v116, v4
	v_mul_f32_e32 v2, v8, v2
	v_bfe_u32 v3, v2, 16, 1
	v_add3_u32 v2, v2, v3, s66
	ds_write_b16_d16_hi v212, v2 offset:2176
	v_mul_f32_e32 v2, v114, v4
	v_mul_f32_e32 v2, v7, v2
	v_bfe_u32 v3, v2, 16, 1
	v_add3_u32 v2, v2, v3, s66
	ds_write_b16_d16_hi v212, v2 offset:2240
	v_mul_f32_e32 v2, v112, v4
	v_mul_f32_e32 v2, v6, v2
	v_bfe_u32 v3, v2, 16, 1
	v_add3_u32 v2, v2, v3, s66
	ds_write_b16_d16_hi v212, v2 offset:2304
	v_mul_f32_e32 v2, v110, v4
	v_mul_f32_e32 v2, v0, v2
	v_bfe_u32 v3, v2, 16, 1
	v_add3_u32 v2, v2, v3, s66
	ds_write_b16_d16_hi v212, v2 offset:2368
	v_mul_f32_e32 v2, v117, v5
	v_mul_f32_e32 v2, v8, v2
	v_bfe_u32 v3, v2, 16, 1
	v_add3_u32 v2, v2, v3, s66
	ds_write_b16_d16_hi v212, v2 offset:2448
	v_mul_f32_e32 v2, v115, v5
	v_mul_f32_e32 v2, v7, v2
	v_bfe_u32 v3, v2, 16, 1
	v_add3_u32 v2, v2, v3, s66
	ds_write_b16_d16_hi v212, v2 offset:2512
	v_mul_f32_e32 v2, v113, v5
	v_mul_f32_e32 v2, v6, v2
	v_bfe_u32 v3, v2, 16, 1
	v_add3_u32 v2, v2, v3, s66
	ds_write_b16_d16_hi v212, v2 offset:2576
	v_mul_f32_e32 v2, v111, v5
	v_mul_f32_e32 v2, v0, v2
	v_bfe_u32 v3, v2, 16, 1
	v_add3_u32 v2, v2, v3, s66
	ds_write_b16_d16_hi v212, v2 offset:2640
	ds_read_b128 v[2:5], v209 offset:96
	s_waitcnt lgkmcnt(0)
	v_mul_f32_e32 v9, v84, v2
	v_mul_f32_e32 v9, v8, v9
	v_bfe_u32 v10, v9, 16, 1
	v_add3_u32 v9, v9, v10, s66
	ds_write_b16_d16_hi v212, v9 offset:3808
	v_mul_f32_e32 v9, v80, v2
	v_mul_f32_e32 v9, v7, v9
	v_bfe_u32 v10, v9, 16, 1
	v_add3_u32 v9, v9, v10, s66
	ds_write_b16_d16_hi v212, v9 offset:3872
	v_mul_f32_e32 v9, v82, v2
	v_mul_f32_e32 v9, v6, v9
	v_bfe_u32 v10, v9, 16, 1
	v_mul_f32_e32 v2, v78, v2
	v_add3_u32 v9, v9, v10, s66
	v_mul_f32_e32 v2, v0, v2
	ds_write_b16_d16_hi v212, v9 offset:3936
	v_bfe_u32 v9, v2, 16, 1
	v_add3_u32 v2, v2, v9, s66
	ds_write_b16_d16_hi v212, v2 offset:4000
	v_mul_f32_e32 v2, v85, v3
	v_mul_f32_e32 v2, v8, v2
	v_bfe_u32 v9, v2, 16, 1
	v_add3_u32 v2, v2, v9, s66
	ds_write_b16_d16_hi v212, v2 offset:4080
	v_mul_f32_e32 v2, v81, v3
	v_mul_f32_e32 v2, v7, v2
	v_bfe_u32 v9, v2, 16, 1
	v_add3_u32 v2, v2, v9, s66
	ds_write_b16_d16_hi v212, v2 offset:4144
	v_mul_f32_e32 v2, v83, v3
	v_mul_f32_e32 v2, v6, v2
	v_bfe_u32 v9, v2, 16, 1
	v_add3_u32 v2, v2, v9, s66
	ds_write_b16_d16_hi v212, v2 offset:4208
	v_mul_f32_e32 v2, v79, v3
	v_mul_f32_e32 v2, v0, v2
	v_bfe_u32 v3, v2, 16, 1
	v_add3_u32 v2, v2, v3, s66
	ds_write_b16_d16_hi v212, v2 offset:4272
	v_mul_f32_e32 v2, v92, v4
	v_mul_f32_e32 v2, v8, v2
	v_bfe_u32 v3, v2, 16, 1
	v_add3_u32 v2, v2, v3, s66
	ds_write_b16_d16_hi v212, v2 offset:4352
	v_mul_f32_e32 v2, v88, v4
	v_mul_f32_e32 v2, v7, v2
	v_bfe_u32 v3, v2, 16, 1
	v_add3_u32 v2, v2, v3, s66
	ds_write_b16_d16_hi v212, v2 offset:4416
	v_mul_f32_e32 v2, v90, v4
	v_mul_f32_e32 v2, v6, v2
	v_bfe_u32 v3, v2, 16, 1
	v_add3_u32 v2, v2, v3, s66
	ds_write_b16_d16_hi v212, v2 offset:4480
	v_mul_f32_e32 v2, v86, v4
	v_mul_f32_e32 v2, v0, v2
	v_bfe_u32 v3, v2, 16, 1
	v_add3_u32 v2, v2, v3, s66
	ds_write_b16_d16_hi v212, v2 offset:4544
	v_mul_f32_e32 v2, v93, v5
	v_mul_f32_e32 v2, v8, v2
	v_bfe_u32 v3, v2, 16, 1
	v_add3_u32 v2, v2, v3, s66
	ds_write_b16_d16_hi v212, v2 offset:4624
	v_mul_f32_e32 v2, v89, v5
	v_mul_f32_e32 v2, v7, v2
	v_bfe_u32 v3, v2, 16, 1
	v_add3_u32 v2, v2, v3, s66
	ds_write_b16_d16_hi v212, v2 offset:4688
	v_mul_f32_e32 v2, v91, v5
	v_mul_f32_e32 v2, v6, v2
	v_bfe_u32 v3, v2, 16, 1
	v_add3_u32 v2, v2, v3, s66
	ds_write_b16_d16_hi v212, v2 offset:4752
	v_mul_f32_e32 v2, v87, v5
	v_mul_f32_e32 v0, v0, v2
	v_bfe_u32 v2, v0, 16, 1
	v_add3_u32 v0, v0, v2, s66
	ds_write_b16_d16_hi v212, v0 offset:4816
	s_waitcnt lgkmcnt(0)
	v_add_u32_e32 v0, v196, v198
	ds_read_b128 v[2:5], v0
	v_add_u32_e32 v6, s52, v194
	v_ashrrev_i32_e32 v7, 31, v6
	v_lshlrev_b64 v[8:9], 12, v[6:7]
	v_lshl_add_u64 v[8:9], v[182:183], 0, v[8:9]
	s_waitcnt lgkmcnt(0)
	global_store_dwordx4 v[8:9], v[2:5], off offset:2048
	ds_read_b128 v[2:5], v213
	v_add_u32_e32 v0, 4, v194
	v_add_u32_e32 v8, s52, v0
	v_ashrrev_i32_e32 v9, 31, v8
	v_lshlrev_b64 v[8:9], 12, v[8:9]
	v_lshl_add_u64 v[8:9], v[182:183], 0, v[8:9]
	s_waitcnt lgkmcnt(0)
	global_store_dwordx4 v[8:9], v[2:5], off offset:2048
	ds_read_b128 v[2:5], v213 offset:1088
	v_add_u32_e32 v8, 8, v6
	v_ashrrev_i32_e32 v9, 31, v8
	v_lshlrev_b64 v[8:9], 12, v[8:9]
	v_lshl_add_u64 v[8:9], v[182:183], 0, v[8:9]
	s_waitcnt lgkmcnt(0)
	global_store_dwordx4 v[8:9], v[2:5], off offset:2048
	ds_read_b128 v[2:5], v213 offset:2176
	v_add_u32_e32 v8, 12, v6
	v_ashrrev_i32_e32 v9, 31, v8
	v_lshlrev_b64 v[8:9], 12, v[8:9]
	v_lshl_add_u64 v[8:9], v[182:183], 0, v[8:9]
	s_waitcnt lgkmcnt(0)
	global_store_dwordx4 v[8:9], v[2:5], off offset:2048
	ds_read_b128 v[2:5], v213 offset:3264
	v_add_u32_e32 v8, 16, v6
	v_ashrrev_i32_e32 v9, 31, v8
	v_lshlrev_b64 v[8:9], 12, v[8:9]
	v_lshl_add_u64 v[8:9], v[182:183], 0, v[8:9]
	s_waitcnt lgkmcnt(0)
	global_store_dwordx4 v[8:9], v[2:5], off offset:2048
	ds_read_b128 v[2:5], v213 offset:4352
	v_add_u32_e32 v8, 20, v6
	v_ashrrev_i32_e32 v9, 31, v8
	v_lshlrev_b64 v[8:9], 12, v[8:9]
	v_lshl_add_u64 v[8:9], v[182:183], 0, v[8:9]
	s_waitcnt lgkmcnt(0)
	global_store_dwordx4 v[8:9], v[2:5], off offset:2048
	ds_read_b128 v[2:5], v213 offset:5440
	v_add_u32_e32 v8, 24, v6
	v_ashrrev_i32_e32 v9, 31, v8
	v_lshlrev_b64 v[8:9], 12, v[8:9]
	v_lshl_add_u64 v[8:9], v[182:183], 0, v[8:9]
	s_waitcnt lgkmcnt(0)
	global_store_dwordx4 v[8:9], v[2:5], off offset:2048
	ds_read_b128 v[2:5], v213 offset:6528
	v_add_u32_e32 v6, 28, v6
	v_ashrrev_i32_e32 v7, 31, v6
	v_lshlrev_b64 v[6:7], 12, v[6:7]
	v_lshl_add_u64 v[6:7], v[182:183], 0, v[6:7]
	s_waitcnt lgkmcnt(0)
	global_store_dwordx4 v[6:7], v[2:5], off offset:2048
	s_cbranch_scc0 .LBB0_826
